# v17 + DN/WO: residual values of the 32 extra rows loaded inside the last MFMA block of the K loop (dead B0 fragment registers) instead of at the start of the extra-row epilogue
# speedup vs baseline: 1.0081x; 1.0003x over previous
; #define PG8_STAGE(bufoff, gbase, voff) do { _Pragma("unroll") for (int _i = 0; _i < 2; ++_i) \
;         __builtin_amdgcn_global_load_lds((const unsigned*)((const char*)(gbase) + (voff)[_i]), (PG8_LAS unsigned*)(lds + (bufoff) + ldsw + _i * 8192), 16, 0, 0); } while (0)
; #define PG8_LDA(dst, b, h) do { _Pragma("unroll") for (int m = 0; m < 4; ++m) _Pragma("unroll") for (int k = 0; k < 2; ++k) dst[m][k] = *(const PG8_LAS bf16x8*)(lds + PG8_SA(b, h) + aoff + m * 2048 + k * 1024); } while (0)
; #define PG8_LDB(dst, b, h) do { _Pragma("unroll") for (int n = 0; n < 2; ++n) _Pragma("unroll") for (int k = 0; k < 2; ++k) dst[n][k] = *(const PG8_LAS bf16x8*)(lds + PG8_SB(b, h) + boff + n * 2048 + k * 1024); } while (0)
; #define PG8_MMA(ai, bj, At, Bt) do { __builtin_amdgcn_s_setprio(1); _Pragma("unroll") for (int m = 0; m < 4; ++m) _Pragma("unroll") for (int n = 0; n < 2; ++n) _Pragma("unroll") for (int k = 0; k < 2; ++k) \
;         acc[ai][bj][m][n] = __builtin_amdgcn_mfma_f32_16x16x32_bf16(Bt[n][k], At[m][k], acc[ai][bj][m][n], 0, 0, 0); __builtin_amdgcn_s_setprio(0); } while (0)
; #define PG8_WAIT_V(n) asm volatile("s_waitcnt vmcnt(" #n ")" ::: "memory")
; #define PG8_WAIT_L(n) asm volatile("s_waitcnt lgkmcnt(" #n ")" ::: "memory")
; #define PG8_BAR __builtin_amdgcn_s_barrier()
; #define PG8_SCHED __builtin_amdgcn_sched_barrier(0)
; template <class Epi, class Sched, bool ALIGN_EPI = false, bool SP2 = false>
; __device__ __forceinline__ void gemm_phase(PG8_LAS unsigned char* lds, const Gemm g, const Sched& S, const Epi& E) {
;     ...
;             const bool last = (t == nt - 2);
;             const char* a1 = cA + (size_t)(t + 1) * kstep;
;             const char* a2 = last ? nA : cA + (size_t)(t + 2) * kstep; const char* b2 = last ? nB : cB + (size_t)(t + 2) * kstep;
;             const char* a3 = a2 + kstep; const char* b3 = b2 + kstep;
;             if (last && has_next) S.a_ready(nxt);
;             if constexpr (SP2) {
;             PG8_LDB(B0, 0, 0); PG8_LDB(B1, 0, 1); PG8_SCHED; PG8_LDA(At, 0, 0); PG8_STAGE(PG8_SA(1, 1), a1 + hstep, voffA);
;             PG8_WAIT_V(8); PG8_WAIT_L(0); PG8_BAR; PG8_MMA(0, 0, At, B0); PG8_MMA(0, 1, At, B1); PG8_BAR; PG8_SCHED;
;             PG8_LDA(At, 0, 1); PG8_STAGE(PG8_SB(0, 0), b2, voffB); PG8_STAGE(PG8_SB(0, 1), b2 + hstep, voffB); PG8_STAGE(PG8_SA(0, 0), a2, voffA);
.LBB0_218:
	s_add_u32 s25, s0, 0xfffc0080
	s_addc_u32 s40, s1, -1
	s_cmp_eq_u32 s93, 12
	s_cselect_b32 s43, s4, s40
	s_cselect_b32 s42, s5, s25
	s_cselect_b32 s41, s27, s92
	s_cselect_b32 s40, s58, s59
	s_add_i32 s94, 0, 0x10000
	s_add_i32 s25, 0, 0x14000
	v_add_u32_e32 v140, s94, v228
	v_add_u32_e32 v156, s25, v228
	ds_read_b128 v[128:131], v140
	ds_read_b128 v[132:135], v140 offset:1024
	ds_read_b128 v[136:139], v140 offset:2048
	ds_read_b128 v[140:143], v140 offset:3072
	ds_read_b128 v[144:147], v156
	ds_read_b128 v[148:151], v156 offset:1024
	ds_read_b128 v[152:155], v156 offset:2048
	ds_read_b128 v[156:159], v156 offset:3072
	s_add_i32 m0, s45, 0xc000
	ds_read_b128 v[160:163], v230
	ds_read_b128 v[164:167], v230 offset:1024
	ds_read_b128 v[168:171], v230 offset:2048
	ds_read_b128 v[172:175], v230 offset:3072
	ds_read_b128 v[176:179], v230 offset:4096
	ds_read_b128 v[180:183], v230 offset:5120
	ds_read_b128 v[204:207], v230 offset:6144
	ds_read_b128 v[208:211], v230 offset:7168
	ds_read_b128 v[212:215], v249
	ds_read_b128 v[232:235], v249 offset:1024
	global_load_lds_dwordx4 v198, s[0:1]
	s_add_i32 m0, s45, 0xe000
	s_nop 0
	global_load_lds_dwordx4 v196, s[0:1]
	s_waitcnt vmcnt(9)
	s_waitcnt lgkmcnt(0)
	s_barrier
	s_setprio 1
	s_waitcnt lgkmcnt(0)
	v_mfma_f32_16x16x32_bf16 v[124:127], v[128:131], v[160:163], v[124:127]
	v_mfma_f32_16x16x32_bf16 v[120:123], v[136:139], v[160:163], v[120:123]
	v_mfma_f32_16x16x32_bf16 v[108:111], v[128:131], v[168:171], v[108:111]
	v_mfma_f32_16x16x32_bf16 v[104:107], v[136:139], v[168:171], v[104:107]
	v_mfma_f32_16x16x32_bf16 v[92:95], v[128:131], v[176:179], v[92:95]
	v_mfma_f32_16x16x32_bf16 v[88:91], v[136:139], v[176:179], v[88:91]
	v_mfma_f32_16x16x32_bf16 v[76:79], v[128:131], v[204:207], v[76:79]
	v_mfma_f32_16x16x32_bf16 v[72:75], v[136:139], v[204:207], v[72:75]
	v_mfma_f32_16x16x32_bf16 v[124:127], v[132:135], v[164:167], v[124:127]
	v_mfma_f32_16x16x32_bf16 v[120:123], v[140:143], v[164:167], v[120:123]
	v_mfma_f32_16x16x32_bf16 v[108:111], v[132:135], v[172:175], v[108:111]
	v_mfma_f32_16x16x32_bf16 v[104:107], v[140:143], v[172:175], v[104:107]
	v_mfma_f32_16x16x32_bf16 v[92:95], v[132:135], v[180:183], v[92:95]
	v_mfma_f32_16x16x32_bf16 v[88:91], v[140:143], v[180:183], v[88:91]
	v_mfma_f32_16x16x32_bf16 v[76:79], v[132:135], v[208:211], v[76:79]
	v_mfma_f32_16x16x32_bf16 v[72:75], v[140:143], v[208:211], v[72:75]
	s_setprio 0
	s_setprio 1
	v_mfma_f32_16x16x32_bf16 v[116:119], v[144:147], v[160:163], v[116:119]
	v_mfma_f32_16x16x32_bf16 v[112:115], v[152:155], v[160:163], v[112:115]
	v_mfma_f32_16x16x32_bf16 v[100:103], v[144:147], v[168:171], v[100:103]
	v_mfma_f32_16x16x32_bf16 v[96:99], v[152:155], v[168:171], v[96:99]
	v_mfma_f32_16x16x32_bf16 v[84:87], v[144:147], v[176:179], v[84:87]
	v_mfma_f32_16x16x32_bf16 v[80:83], v[152:155], v[176:179], v[80:83]
	v_mfma_f32_16x16x32_bf16 v[68:71], v[144:147], v[204:207], v[68:71]
	v_mfma_f32_16x16x32_bf16 v[64:67], v[152:155], v[204:207], v[64:67]
	v_mfma_f32_16x16x32_bf16 v[116:119], v[148:151], v[164:167], v[116:119]
	v_mfma_f32_16x16x32_bf16 v[112:115], v[156:159], v[164:167], v[112:115]
	v_mfma_f32_16x16x32_bf16 v[100:103], v[148:151], v[172:175], v[100:103]
	v_mfma_f32_16x16x32_bf16 v[96:99], v[156:159], v[172:175], v[96:99]
	v_mfma_f32_16x16x32_bf16 v[84:87], v[148:151], v[180:183], v[84:87]
	v_mfma_f32_16x16x32_bf16 v[80:83], v[156:159], v[180:183], v[80:83]
	v_mfma_f32_16x16x32_bf16 v[68:71], v[148:151], v[208:211], v[68:71]
	v_mfma_f32_16x16x32_bf16 v[64:67], v[156:159], v[208:211], v[64:67]
	v_mfma_f32_16x16x32_bf16 v[236:239], v[128:131], v[212:215], v[236:239]
	v_mfma_f32_16x16x32_bf16 v[240:243], v[136:139], v[212:215], v[240:243]
	v_mfma_f32_16x16x32_bf16 v[244:247], v[144:147], v[212:215], v[244:247]
	v_mfma_f32_16x16x32_bf16 v[200:203], v[152:155], v[212:215], v[200:203]
	v_mfma_f32_16x16x32_bf16 v[236:239], v[132:135], v[232:235], v[236:239]
	v_mfma_f32_16x16x32_bf16 v[240:243], v[140:143], v[232:235], v[240:243]
	v_mfma_f32_16x16x32_bf16 v[244:247], v[148:151], v[232:235], v[244:247]
	v_mfma_f32_16x16x32_bf16 v[200:203], v[156:159], v[232:235], v[200:203]
	s_setprio 0
	s_barrier
	s_add_i32 s94, s94, s44
	s_mov_b32 m0, s94
	ds_read_b128 v[160:163], v230 offset:16384
	ds_read_b128 v[164:167], v230 offset:17408
	ds_read_b128 v[168:171], v230 offset:18432
	ds_read_b128 v[172:175], v230 offset:19456
	ds_read_b128 v[176:179], v230 offset:20480
	ds_read_b128 v[180:183], v230 offset:21504
	ds_read_b128 v[204:207], v230 offset:22528
	ds_read_b128 v[208:211], v230 offset:23552
	global_load_lds_dwordx4 v184, s[40:41]
	s_add_i32 m0, s94, 0x2000
	s_add_u32 s98, s40, 0x40000
	s_addc_u32 s99, s41, 0
	s_add_i32 s25, s25, s44
	global_load_lds_dwordx4 v194, s[40:41]
	s_mov_b32 m0, s25
	s_nop 0
	global_load_lds_dwordx4 v184, s[98:99]
	s_add_i32 m0, s25, 0x2000
	s_nop 0
	global_load_lds_dwordx4 v194, s[98:99]
	s_mov_b32 m0, s45
	s_nop 0
	global_load_lds_dwordx4 v198, s[42:43]
	s_mov_b32 m0, s46
	s_nop 0
	global_load_lds_dwordx4 v196, s[42:43]
	s_and_b32 m0, s44, 0xc00
	s_add_i32 m0, m0, 0x20800
	s_nop 0
	global_load_lds_dwordx4 v248, s[42:43]
	s_nop 0
	s_waitcnt vmcnt(9)
	s_waitcnt lgkmcnt(0)
	s_barrier
; #define PG8_STAGE(bufoff, gbase, voff) do { _Pragma("unroll") for (int _i = 0; _i < 2; ++_i) \
;         __builtin_amdgcn_global_load_lds((const unsigned*)((const char*)(gbase) + (voff)[_i]), (PG8_LAS unsigned*)(lds + (bufoff) + ldsw + _i * 8192), 16, 0, 0); } while (0)
; #define PG8_LDA(dst, b, h) do { _Pragma("unroll") for (int m = 0; m < 4; ++m) _Pragma("unroll") for (int k = 0; k < 2; ++k) dst[m][k] = *(const PG8_LAS bf16x8*)(lds + PG8_SA(b, h) + aoff + m * 2048 + k * 1024); } while (0)
; #define PG8_LDB(dst, b, h) do { _Pragma("unroll") for (int n = 0; n < 2; ++n) _Pragma("unroll") for (int k = 0; k < 2; ++k) dst[n][k] = *(const PG8_LAS bf16x8*)(lds + PG8_SB(b, h) + boff + n * 2048 + k * 1024); } while (0)
; #define PG8_MMA(ai, bj, At, Bt) do { __builtin_amdgcn_s_setprio(1); _Pragma("unroll") for (int m = 0; m < 4; ++m) _Pragma("unroll") for (int n = 0; n < 2; ++n) _Pragma("unroll") for (int k = 0; k < 2; ++k) \
;         acc[ai][bj][m][n] = __builtin_amdgcn_mfma_f32_16x16x32_bf16(Bt[n][k], At[m][k], acc[ai][bj][m][n], 0, 0, 0); __builtin_amdgcn_s_setprio(0); } while (0)
; #define PG8_WAIT_V(n) asm volatile("s_waitcnt vmcnt(" #n ")" ::: "memory")
; #define PG8_WAIT_L(n) asm volatile("s_waitcnt lgkmcnt(" #n ")" ::: "memory")
; #define PG8_BAR __builtin_amdgcn_s_barrier()
; #define PG8_SCHED __builtin_amdgcn_sched_barrier(0)
; template <class Epi, class Sched, bool ALIGN_EPI = false, bool SP2 = false>
; __device__ __forceinline__ void gemm_phase(PG8_LAS unsigned char* lds, const Gemm g, const Sched& S, const Epi& E) {
;     ...
;             PG8_WAIT_V(8); PG8_WAIT_L(0); PG8_BAR; PG8_MMA(1, 0, At, B0); PG8_MMA(1, 1, At, B1); PG8_BAR; PG8_SCHED;
;             PG8_LDB(B0, 1, 0); PG8_LDB(B1, 1, 1); PG8_SCHED; PG8_LDA(At, 1, 0); PG8_STAGE(PG8_SA(0, 1), a2 + hstep, voffA);
;             PG8_WAIT_V(8); PG8_WAIT_L(0); PG8_BAR; PG8_MMA(0, 0, At, B0); PG8_MMA(0, 1, At, B1); PG8_BAR; PG8_SCHED;
	s_setprio 1
	s_waitcnt lgkmcnt(0)
	v_mfma_f32_16x16x32_bf16 v[60:63], v[128:131], v[160:163], v[60:63]
	v_mfma_f32_16x16x32_bf16 v[56:59], v[136:139], v[160:163], v[56:59]
	v_mfma_f32_16x16x32_bf16 v[44:47], v[128:131], v[168:171], v[44:47]
	v_mfma_f32_16x16x32_bf16 v[40:43], v[136:139], v[168:171], v[40:43]
	v_mfma_f32_16x16x32_bf16 v[28:31], v[128:131], v[176:179], v[28:31]
	v_mfma_f32_16x16x32_bf16 v[24:27], v[136:139], v[176:179], v[24:27]
	v_mfma_f32_16x16x32_bf16 v[12:15], v[128:131], v[204:207], v[12:15]
	v_mfma_f32_16x16x32_bf16 v[8:11], v[136:139], v[204:207], v[8:11]
	v_mfma_f32_16x16x32_bf16 v[60:63], v[132:135], v[164:167], v[60:63]
	v_mfma_f32_16x16x32_bf16 v[56:59], v[140:143], v[164:167], v[56:59]
	v_mfma_f32_16x16x32_bf16 v[44:47], v[132:135], v[172:175], v[44:47]
	v_mfma_f32_16x16x32_bf16 v[40:43], v[140:143], v[172:175], v[40:43]
	v_mfma_f32_16x16x32_bf16 v[28:31], v[132:135], v[180:183], v[28:31]
	v_mfma_f32_16x16x32_bf16 v[24:27], v[140:143], v[180:183], v[24:27]
	v_mfma_f32_16x16x32_bf16 v[12:15], v[132:135], v[208:211], v[12:15]
	v_mfma_f32_16x16x32_bf16 v[8:11], v[140:143], v[208:211], v[8:11]
	s_setprio 0
	s_setprio 1
	v_mfma_f32_16x16x32_bf16 v[52:55], v[144:147], v[160:163], v[52:55]
	v_mfma_f32_16x16x32_bf16 v[48:51], v[152:155], v[160:163], v[48:51]
	v_mfma_f32_16x16x32_bf16 v[36:39], v[144:147], v[168:171], v[36:39]
	v_mfma_f32_16x16x32_bf16 v[32:35], v[152:155], v[168:171], v[32:35]
	v_mfma_f32_16x16x32_bf16 v[20:23], v[144:147], v[176:179], v[20:23]
	v_mfma_f32_16x16x32_bf16 v[16:19], v[152:155], v[176:179], v[16:19]
	v_mfma_f32_16x16x32_bf16 v[4:7], v[144:147], v[204:207], v[4:7]
	v_mfma_f32_16x16x32_bf16 v[0:3], v[152:155], v[204:207], v[0:3]
	v_mfma_f32_16x16x32_bf16 v[52:55], v[148:151], v[164:167], v[52:55]
	v_mfma_f32_16x16x32_bf16 v[48:51], v[156:159], v[164:167], v[48:51]
	v_mfma_f32_16x16x32_bf16 v[36:39], v[148:151], v[172:175], v[36:39]
	v_mfma_f32_16x16x32_bf16 v[32:35], v[156:159], v[172:175], v[32:35]
	v_mfma_f32_16x16x32_bf16 v[20:23], v[148:151], v[180:183], v[20:23]
	v_mfma_f32_16x16x32_bf16 v[16:19], v[156:159], v[180:183], v[16:19]
	v_mfma_f32_16x16x32_bf16 v[4:7], v[148:151], v[208:211], v[4:7]
	v_mfma_f32_16x16x32_bf16 v[0:3], v[156:159], v[208:211], v[0:3]
	s_setprio 0
	s_barrier
	s_add_i32 s25, 0, 0x18000
	s_add_i32 s94, 0, 0x1c000
	v_add_u32_e32 v140, s25, v228
	v_add_u32_e32 v156, s94, v228
	ds_read_b128 v[128:131], v140
	ds_read_b128 v[132:135], v140 offset:1024
	ds_read_b128 v[136:139], v140 offset:2048
	ds_read_b128 v[140:143], v140 offset:3072
	ds_read_b128 v[144:147], v156
	ds_read_b128 v[148:151], v156 offset:1024
	ds_read_b128 v[152:155], v156 offset:2048
	ds_read_b128 v[156:159], v156 offset:3072
	s_add_u32 s98, s42, 0x40000
	s_addc_u32 s99, s43, 0
	s_mov_b32 m0, s47
	ds_read_b128 v[160:163], v230 offset:32768
	ds_read_b128 v[164:167], v230 offset:33792
	ds_read_b128 v[168:171], v230 offset:34816
	ds_read_b128 v[172:175], v230 offset:35840
	ds_read_b128 v[176:179], v230 offset:36864
	ds_read_b128 v[180:183], v230 offset:37888
	ds_read_b128 v[204:207], v230 offset:38912
	ds_read_b128 v[208:211], v230 offset:39936
	ds_read_b128 v[212:215], v249 offset:4096
	ds_read_b128 v[232:235], v249 offset:5120
	global_load_lds_dwordx4 v198, s[98:99]
	s_mov_b32 m0, s48
	s_nop 0
	global_load_lds_dwordx4 v196, s[98:99]
	s_nop 0
	s_waitcnt vmcnt(9)
	s_waitcnt lgkmcnt(0)
	s_barrier
	s_setprio 1
	s_waitcnt lgkmcnt(0)
	v_mfma_f32_16x16x32_bf16 v[124:127], v[128:131], v[160:163], v[124:127]
	v_mfma_f32_16x16x32_bf16 v[120:123], v[136:139], v[160:163], v[120:123]
	v_mfma_f32_16x16x32_bf16 v[108:111], v[128:131], v[168:171], v[108:111]
	v_mfma_f32_16x16x32_bf16 v[104:107], v[136:139], v[168:171], v[104:107]
	v_mfma_f32_16x16x32_bf16 v[92:95], v[128:131], v[176:179], v[92:95]
	v_mfma_f32_16x16x32_bf16 v[88:91], v[136:139], v[176:179], v[88:91]
	v_mfma_f32_16x16x32_bf16 v[76:79], v[128:131], v[204:207], v[76:79]
	v_mfma_f32_16x16x32_bf16 v[72:75], v[136:139], v[204:207], v[72:75]
	v_mfma_f32_16x16x32_bf16 v[124:127], v[132:135], v[164:167], v[124:127]
	v_mfma_f32_16x16x32_bf16 v[120:123], v[140:143], v[164:167], v[120:123]
	v_mfma_f32_16x16x32_bf16 v[108:111], v[132:135], v[172:175], v[108:111]
	v_mfma_f32_16x16x32_bf16 v[104:107], v[140:143], v[172:175], v[104:107]
	v_mfma_f32_16x16x32_bf16 v[92:95], v[132:135], v[180:183], v[92:95]
	v_mfma_f32_16x16x32_bf16 v[88:91], v[140:143], v[180:183], v[88:91]
	v_mfma_f32_16x16x32_bf16 v[76:79], v[132:135], v[208:211], v[76:79]
	v_mfma_f32_16x16x32_bf16 v[72:75], v[140:143], v[208:211], v[72:75]
	s_setprio 0
	s_setprio 1
	v_mfma_f32_16x16x32_bf16 v[116:119], v[144:147], v[160:163], v[116:119]
	v_mfma_f32_16x16x32_bf16 v[112:115], v[152:155], v[160:163], v[112:115]
	v_mfma_f32_16x16x32_bf16 v[100:103], v[144:147], v[168:171], v[100:103]
	v_mfma_f32_16x16x32_bf16 v[96:99], v[152:155], v[168:171], v[96:99]
	v_mfma_f32_16x16x32_bf16 v[84:87], v[144:147], v[176:179], v[84:87]
	v_mfma_f32_16x16x32_bf16 v[80:83], v[152:155], v[176:179], v[80:83]
	v_mfma_f32_16x16x32_bf16 v[68:71], v[144:147], v[204:207], v[68:71]
	v_mfma_f32_16x16x32_bf16 v[64:67], v[152:155], v[204:207], v[64:67]
	v_mfma_f32_16x16x32_bf16 v[116:119], v[148:151], v[164:167], v[116:119]
	v_mfma_f32_16x16x32_bf16 v[112:115], v[156:159], v[164:167], v[112:115]
	v_mfma_f32_16x16x32_bf16 v[100:103], v[148:151], v[172:175], v[100:103]
	v_mfma_f32_16x16x32_bf16 v[96:99], v[156:159], v[172:175], v[96:99]
	v_mfma_f32_16x16x32_bf16 v[84:87], v[148:151], v[180:183], v[84:87]
	v_mfma_f32_16x16x32_bf16 v[80:83], v[156:159], v[180:183], v[80:83]
	v_mfma_f32_16x16x32_bf16 v[68:71], v[148:151], v[208:211], v[68:71]
	v_mfma_f32_16x16x32_bf16 v[64:67], v[156:159], v[208:211], v[64:67]
	v_mfma_f32_16x16x32_bf16 v[236:239], v[128:131], v[212:215], v[236:239]
	v_mfma_f32_16x16x32_bf16 v[240:243], v[136:139], v[212:215], v[240:243]
	v_mfma_f32_16x16x32_bf16 v[244:247], v[144:147], v[212:215], v[244:247]
	v_mfma_f32_16x16x32_bf16 v[200:203], v[152:155], v[212:215], v[200:203]
	v_mfma_f32_16x16x32_bf16 v[236:239], v[132:135], v[232:235], v[236:239]
	v_mfma_f32_16x16x32_bf16 v[240:243], v[140:143], v[232:235], v[240:243]
	v_mfma_f32_16x16x32_bf16 v[244:247], v[148:151], v[232:235], v[244:247]
	v_mfma_f32_16x16x32_bf16 v[200:203], v[156:159], v[232:235], v[200:203]
	s_setprio 0
	s_barrier
; #define PG8_STAGE(bufoff, gbase, voff) do { _Pragma("unroll") for (int _i = 0; _i < 2; ++_i) \
;         __builtin_amdgcn_global_load_lds((const unsigned*)((const char*)(gbase) + (voff)[_i]), (PG8_LAS unsigned*)(lds + (bufoff) + ldsw + _i * 8192), 16, 0, 0); } while (0)
; #define PG8_LDA(dst, b, h) do { _Pragma("unroll") for (int m = 0; m < 4; ++m) _Pragma("unroll") for (int k = 0; k < 2; ++k) dst[m][k] = *(const PG8_LAS bf16x8*)(lds + PG8_SA(b, h) + aoff + m * 2048 + k * 1024); } while (0)
; #define PG8_MMA(ai, bj, At, Bt) do { __builtin_amdgcn_s_setprio(1); _Pragma("unroll") for (int m = 0; m < 4; ++m) _Pragma("unroll") for (int n = 0; n < 2; ++n) _Pragma("unroll") for (int k = 0; k < 2; ++k) \
;         acc[ai][bj][m][n] = __builtin_amdgcn_mfma_f32_16x16x32_bf16(Bt[n][k], At[m][k], acc[ai][bj][m][n], 0, 0, 0); __builtin_amdgcn_s_setprio(0); } while (0)
; #define PG8_WAIT_V(n) asm volatile("s_waitcnt vmcnt(" #n ")" ::: "memory")
; #define PG8_WAIT_L(n) asm volatile("s_waitcnt lgkmcnt(" #n ")" ::: "memory")
; #define PG8_BAR __builtin_amdgcn_s_barrier()
; #define PG8_SCHED __builtin_amdgcn_sched_barrier(0)
; template <class Epi, class Sched, bool ALIGN_EPI = false, bool SP2 = false>
; __device__ __forceinline__ void gemm_phase(PG8_LAS unsigned char* lds, const Gemm g, const Sched& S, const Epi& E) {
;     ...
;             PG8_LDA(At, 1, 1); PG8_STAGE(PG8_SB(1, 0), b3, voffB); PG8_STAGE(PG8_SB(1, 1), b3 + hstep, voffB); PG8_STAGE(PG8_SA(1, 0), a3, voffA);
;             PG8_WAIT_V(8); PG8_WAIT_L(0); PG8_BAR; PG8_MMA(1, 0, At, B0); PG8_MMA(1, 1, At, B1); PG8_BAR; PG8_SCHED;
; __device__ __forceinline__ void small_gemm_res(LAS unsigned char* lds, const bf16* A, const bf16* Bt, int K, const float* base_s, float* out, bf16* AB, float* PS, int sm, int sn, int tid_in) {
;     ...
;     f32x4 bv[2][2];
; #pragma unroll
;     for (int m_ = 0; m_ < 2; ++m_)
; #pragma unroll
;         for (int n = 0; n < 2; ++n) bv[m_][n] = *(const f32x4*)(base_s + (size_t)(row0 + wr * 32 + m_ * 16 + fr - MP) * D + col0 + wc * 32 + n * 16 + 4 * fq);
	s_add_i32 s25, s25, s44
	s_add_u32 s98, s40, 0x80
	s_addc_u32 s99, s41, 0
	s_mov_b32 m0, s25
	ds_read_b128 v[160:163], v230 offset:49152
	ds_read_b128 v[164:167], v230 offset:50176
	ds_read_b128 v[168:171], v230 offset:51200
	ds_read_b128 v[172:175], v230 offset:52224
	ds_read_b128 v[176:179], v230 offset:53248
	ds_read_b128 v[180:183], v230 offset:54272
	ds_read_b128 v[204:207], v230 offset:55296
	ds_read_b128 v[208:211], v230 offset:56320
	global_load_lds_dwordx4 v184, s[98:99]
	s_add_i32 m0, s25, 0x2000
	s_add_u32 s100, s40, 0x40080
	s_addc_u32 s101, s41, 0
	s_add_i32 s94, s94, s44
	global_load_lds_dwordx4 v194, s[98:99]
	s_mov_b32 m0, s94
	s_add_u32 s98, s42, 0x80
	s_addc_u32 s99, s43, 0
	global_load_lds_dwordx4 v184, s[100:101]
	s_add_i32 m0, s94, 0x2000
	s_nop 0
	global_load_lds_dwordx4 v194, s[100:101]
	s_mov_b32 m0, s51
	s_nop 0
	global_load_lds_dwordx4 v198, s[98:99]
	s_mov_b32 m0, s52
	s_nop 0
	global_load_lds_dwordx4 v196, s[98:99]
	s_and_b32 m0, s44, 0xc00
	s_add_i32 m0, m0, 0x21800
	s_nop 0
	global_load_lds_dwordx4 v248, s[98:99]
	s_waitcnt vmcnt(9)
	s_waitcnt lgkmcnt(0)
	s_barrier
	s_setprio 1
	s_waitcnt lgkmcnt(0)
	v_mfma_f32_16x16x32_bf16 v[60:63], v[128:131], v[160:163], v[60:63]
	v_mfma_f32_16x16x32_bf16 v[56:59], v[136:139], v[160:163], v[56:59]
	v_mfma_f32_16x16x32_bf16 v[44:47], v[128:131], v[168:171], v[44:47]
	v_mfma_f32_16x16x32_bf16 v[40:43], v[136:139], v[168:171], v[40:43]
	v_mfma_f32_16x16x32_bf16 v[28:31], v[128:131], v[176:179], v[28:31]
	v_mfma_f32_16x16x32_bf16 v[24:27], v[136:139], v[176:179], v[24:27]
	v_mfma_f32_16x16x32_bf16 v[12:15], v[128:131], v[204:207], v[12:15]
	v_mfma_f32_16x16x32_bf16 v[8:11], v[136:139], v[204:207], v[8:11]
	v_mfma_f32_16x16x32_bf16 v[60:63], v[132:135], v[164:167], v[60:63]
	v_mfma_f32_16x16x32_bf16 v[56:59], v[140:143], v[164:167], v[56:59]
	v_mfma_f32_16x16x32_bf16 v[44:47], v[132:135], v[172:175], v[44:47]
	v_mfma_f32_16x16x32_bf16 v[40:43], v[140:143], v[172:175], v[40:43]
	v_mfma_f32_16x16x32_bf16 v[28:31], v[132:135], v[180:183], v[28:31]
	v_mfma_f32_16x16x32_bf16 v[24:27], v[140:143], v[180:183], v[24:27]
	v_mfma_f32_16x16x32_bf16 v[12:15], v[132:135], v[208:211], v[12:15]
	v_mfma_f32_16x16x32_bf16 v[8:11], v[140:143], v[208:211], v[8:11]
	s_setprio 0
	s_cmp_eq_u32 s93, 12
	s_cbranch_scc0 .Lxr_skip_218
	s_mul_i32 s98, s56, 0x120
	s_addk_i32 s98, 0x100
	v_and_b32_e32 v190, 15, v227
	v_lshrrev_b32_e32 v191, 6, v227
	v_lshl_add_u32 v190, v191, 4, v190
	v_add_u32_e32 v190, s98, v190
	s_cmp_lt_i32 s56, 56
	s_cselect_b32 s98, s50, s34
	s_cselect_b32 s99, s49, s7
	s_cselect_b32 s100, 0, 0x4000
	v_subrev_u32_e32 v190, s100, v190
	v_mov_b32_e32 v191, 0
	v_lshlrev_b64 v[190:191], 12, v[190:191]
	v_lshl_add_u64 v[190:191], s[98:99], 0, v[190:191]
	v_lshl_or_b32 v217, s57, 8, v229
	v_lshlrev_b32_e32 v217, 2, v217
	v_add_co_u32_e32 v190, vcc, v190, v217
	s_nop 1
	v_addc_co_u32_e32 v191, vcc, 0, v191, vcc
	global_load_dwordx4 v[128:131], v[190:191], off
	global_load_dwordx4 v[132:135], v[190:191], off offset:16
	global_load_dwordx4 v[136:139], v[190:191], off offset:512
	global_load_dwordx4 v[140:143], v[190:191], off offset:528
.Lxr_skip_218:
	s_setprio 1
	v_mfma_f32_16x16x32_bf16 v[52:55], v[144:147], v[160:163], v[52:55]
	v_mfma_f32_16x16x32_bf16 v[48:51], v[152:155], v[160:163], v[48:51]
	v_mfma_f32_16x16x32_bf16 v[36:39], v[144:147], v[168:171], v[36:39]
	v_mfma_f32_16x16x32_bf16 v[32:35], v[152:155], v[168:171], v[32:35]
	v_mfma_f32_16x16x32_bf16 v[20:23], v[144:147], v[176:179], v[20:23]
	v_mfma_f32_16x16x32_bf16 v[16:19], v[152:155], v[176:179], v[16:19]
	v_mfma_f32_16x16x32_bf16 v[4:7], v[144:147], v[204:207], v[4:7]
	v_mfma_f32_16x16x32_bf16 v[0:3], v[152:155], v[204:207], v[0:3]
	v_mfma_f32_16x16x32_bf16 v[52:55], v[148:151], v[164:167], v[52:55]
	v_mfma_f32_16x16x32_bf16 v[48:51], v[156:159], v[164:167], v[48:51]
	v_mfma_f32_16x16x32_bf16 v[36:39], v[148:151], v[172:175], v[36:39]
	v_mfma_f32_16x16x32_bf16 v[32:35], v[156:159], v[172:175], v[32:35]
	v_mfma_f32_16x16x32_bf16 v[20:23], v[148:151], v[180:183], v[20:23]
	v_mfma_f32_16x16x32_bf16 v[16:19], v[156:159], v[180:183], v[16:19]
	v_mfma_f32_16x16x32_bf16 v[4:7], v[148:151], v[208:211], v[4:7]
	v_mfma_f32_16x16x32_bf16 v[0:3], v[156:159], v[208:211], v[0:3]
	s_setprio 0
	s_barrier
	s_add_i32 s93, s93, 2
	s_add_u32 s0, s0, 0x100
	s_addc_u32 s1, s1, 0
	s_add_u32 s59, s59, 0x100
	s_addc_u32 s92, s92, 0
	s_cmp_gt_u32 s93, 13
	s_cbranch_scc0 .LBB0_218
	s_and_b64 vcc, exec, s[20:21]
	s_cbranch_vccz .LBB0_221
	s_barrier
.LBB0_221:
	s_mul_i32 s98, s56, 0x120
	v_and_b32_e32 v144, 15, v227
	v_lshrrev_b32_e32 v145, 6, v227
	v_lshl_add_u32 v144, v145, 4, v144
	v_add_u32_e32 v144, s98, v144
	v_add_u32_e32 v144, 0x100, v144
	v_mov_b32_e32 v145, 0
	v_lshl_or_b32 v146, s57, 8, v229
	v_mov_b32_e32 v147, 0
	s_cmp_lt_i32 s56, 56
	s_cselect_b32 s98, s50, s34
	s_cselect_b32 s99, s49, s7
	s_cselect_b32 s100, 0, 0x4000
	v_subrev_u32_e32 v166, s100, v144
	v_mov_b32_e32 v167, 0
	v_lshlrev_b64 v[166:167], 12, v[166:167]
	v_lshl_add_u64 v[166:167], s[98:99], 0, v[166:167]
	v_lshl_add_u64 v[166:167], v[146:147], 2, v[166:167]


; __device__ __forceinline__ float quad_sum(float s) { s += __shfl_xor(s, 16); s += __shfl_xor(s, 32); return s; }
; __device__ __forceinline__ float sq4(const f32x4 a) { return (a[0] * a[0] + a[1] * a[1]) + (a[2] * a[2] + a[3] * a[3]); }
; __device__ __forceinline__ unsigned pk2(float lo, float hi) { return pg8::cvt_pk_bf16(lo, hi); }
;     __device__ __forceinline__ void operator()(const f32x4 (&acc)[2][2][4][2], const Unit& u, int wr, int wc, int fr, int fq) const {
;     ...
;                 const int row = u.pm * BM + ai * HALF + wr * 64 + m * 16 + fr;
;                 const float* bp = (u.pm < 64) ? base_p + (size_t)row * 1024 : base_s + (size_t)(row - E_MP) * 1024;
; #pragma unroll
;                 for (int bj = 0; bj < 2; ++bj) { bv[m][bj][0] = *(const f32x4*)(bp + col0 + bj * HALF); bv[m][bj][1] = *(const f32x4*)(bp + col0 + bj * HALF + 4); }
; __device__ __forceinline__ void small_gemm_res(LAS unsigned char* lds, const bf16* A, const bf16* Bt, int K, const float* base_s, float* out, bf16* AB, float* PS, int sm, int sn, int tid_in) {
;     ...
; #pragma unroll
;     for (int m_ = 0; m_ < 2; ++m_) {
;         const int rl = wr * 32 + m_ * 16 + fr, row = row0 + rl;
;         float ss = 0.f;
; #pragma unroll
;         for (int n = 0; n < 2; ++n) {
;             const int c = col0 + wc * 32 + n * 16 + 4 * fq;
;             const f32x4 y = bv[m_][n] + acc[m_][n];
;             *(f32x4*)(out + (size_t)row * D + c) = y;
;             *(v2u*)(AB + (size_t)row * D + c) = (v2u){pk2(y[0], y[1]), pk2(y[2], y[3])};
;             ss += pg8::sq4(y);
;         }
;         ss = pg8::quad_sum(ss);
;         if (fq == 0) red[rl * 4 + wc] = ss;
;     }
	v_lshlrev_b64 v[148:149], 12, v[144:145]
	v_lshl_add_u64 v[148:149], s[74:75], 0, v[148:149]
	v_lshl_add_u64 v[148:149], v[146:147], 2, v[148:149]
	v_lshlrev_b64 v[150:151], 11, v[144:145]
	v_lshl_add_u64 v[150:151], s[14:15], 0, v[150:151]
	v_lshl_add_u64 v[150:151], v[146:147], 1, v[150:151]
	s_lshl_b32 s98, s57, 4
	s_add_u32 s98, s54, s98
	s_addc_u32 s99, s55, 0
	v_lshlrev_b64 v[164:165], 6, v[144:145]
	v_lshl_add_u64 v[164:165], s[98:99], 0, v[164:165]
	v_xor_b32_e32 v162, 16, v222
	v_lshlrev_b32_e32 v162, 2, v162
	v_xor_b32_e32 v163, 32, v222
	v_lshlrev_b32_e32 v163, 2, v163
	s_waitcnt vmcnt(0)
	v_pk_add_f32 v[128:129], v[236:237], v[128:129]
	v_pk_add_f32 v[130:131], v[238:239], v[130:131]
	v_pk_add_f32 v[132:133], v[240:241], v[132:133]
	v_pk_add_f32 v[134:135], v[242:243], v[134:135]
	v_pk_add_f32 v[136:137], v[244:245], v[136:137]
	v_pk_add_f32 v[138:139], v[246:247], v[138:139]
	v_pk_add_f32 v[140:141], v[200:201], v[140:141]
	v_pk_add_f32 v[142:143], v[202:203], v[142:143]
	global_store_dwordx4 v[148:149], v[128:131], off
	global_store_dwordx4 v[148:149], v[132:135], off offset:16
	global_store_dwordx4 v[148:149], v[136:139], off offset:512
	global_store_dwordx4 v[148:149], v[140:143], off offset:528
	v_cvt_pk_bf16_f32 v152, v128, v129
	v_cvt_pk_bf16_f32 v153, v130, v131
	v_cvt_pk_bf16_f32 v154, v132, v133
	v_cvt_pk_bf16_f32 v155, v134, v135
	v_cvt_pk_bf16_f32 v156, v136, v137
	v_cvt_pk_bf16_f32 v157, v138, v139
	v_cvt_pk_bf16_f32 v158, v140, v141
	v_cvt_pk_bf16_f32 v159, v142, v143
	global_store_dwordx4 v[150:151], v[152:155], off
	global_store_dwordx4 v[150:151], v[156:159], off offset:256
	v_mul_f32_e32 v160, v128, v128
	v_fmac_f32_e32 v160, v129, v129
	v_fmac_f32_e32 v160, v130, v130
	v_fmac_f32_e32 v160, v131, v131
	v_fmac_f32_e32 v160, v132, v132
	v_fmac_f32_e32 v160, v133, v133
	v_fmac_f32_e32 v160, v134, v134
	v_fmac_f32_e32 v160, v135, v135
	v_fmac_f32_e32 v160, v136, v136
	v_fmac_f32_e32 v160, v137, v137
	v_fmac_f32_e32 v160, v138, v138
	v_fmac_f32_e32 v160, v139, v139
	v_fmac_f32_e32 v160, v140, v140
	v_fmac_f32_e32 v160, v141, v141
	v_fmac_f32_e32 v160, v142, v142
	v_fmac_f32_e32 v160, v143, v143
	ds_bpermute_b32 v161, v162, v160
	s_waitcnt lgkmcnt(0)
	v_add_f32_e32 v160, v160, v161
	ds_bpermute_b32 v161, v163, v160
	s_waitcnt lgkmcnt(0)
	v_add_f32_e32 v160, v160, v161
	s_and_saveexec_b64 s[98:99], s[36:37]
	global_store_dword v[164:165], v160, off
	s_or_b64 exec, exec, s[98:99]
	s_lshl_b32 s0, s57, 2
	s_ashr_i32 s1, s0, 31
	s_lshl_b64 s[0:1], s[0:1], 2
	s_add_u32 s40, s54, s0
	s_addc_u32 s41, s55, s1
	s_mul_i32 s98, s56, 0x120
	v_add_u32_e32 v208, s98, v227
	s_cmp_lt_i32 s56, 57
	s_cselect_b64 vcc, -1, 0
	v_add_u32_e32 v128, 0xffffc000, v208
	v_cndmask_b32_e32 v128, v128, v208, vcc
	v_lshl_or_b32 v204, s57, 8, v229
	s_and_b64 s[0:1], vcc, exec
	v_ashrrev_i32_e32 v129, 31, v128
	v_ashrrev_i32_e32 v205, 31, v204
	s_cselect_b32 s43, s49, s7
	s_cselect_b32 s42, s50, s34
	v_lshlrev_b64 v[128:129], 12, v[128:129]
	v_lshl_add_u64 v[128:129], s[42:43], 0, v[128:129]
	v_lshlrev_b64 v[206:207], 2, v[204:205]
	v_lshl_add_u64 v[128:129], v[128:129], 0, v[206:207]
	global_load_dwordx4 v[232:235], v[128:129], off offset:16
	global_load_dwordx4 v[236:239], v[128:129], off
	global_load_dwordx4 v[176:179], v[128:129], off offset:528
	global_load_dwordx4 v[180:183], v[128:129], off offset:512
	v_add_u32_e32 v214, 16, v208
	v_add_u32_e32 v128, 0xffffc010, v208
	v_cndmask_b32_e32 v128, v128, v214, vcc
	v_ashrrev_i32_e32 v129, 31, v128
	v_lshlrev_b64 v[128:129], 12, v[128:129]
	v_lshl_add_u64 v[128:129], s[42:43], 0, v[128:129]
	v_lshl_add_u64 v[128:129], v[128:129], 0, v[206:207]
	global_load_dwordx4 v[168:171], v[128:129], off offset:16
	global_load_dwordx4 v[172:175], v[128:129], off
	global_load_dwordx4 v[160:163], v[128:129], off offset:528
	global_load_dwordx4 v[164:167], v[128:129], off offset:512
	v_add_u32_e32 v212, 32, v208
	v_add_u32_e32 v128, 0xffffc020, v208
	v_cndmask_b32_e32 v128, v128, v212, vcc
	v_ashrrev_i32_e32 v129, 31, v128
	v_lshlrev_b64 v[128:129], 12, v[128:129]
	v_lshl_add_u64 v[128:129], s[42:43], 0, v[128:129]
	v_lshl_add_u64 v[128:129], v[128:129], 0, v[206:207]
	global_load_dwordx4 v[152:155], v[128:129], off offset:16
	global_load_dwordx4 v[156:159], v[128:129], off
	global_load_dwordx4 v[136:139], v[128:129], off offset:528
	global_load_dwordx4 v[140:143], v[128:129], off offset:512
	v_add_u32_e32 v210, 48, v208
	v_add_u32_e32 v128, 0xffffc030, v208
	v_cndmask_b32_e32 v128, v128, v210, vcc
	v_ashrrev_i32_e32 v129, 31, v128
	v_lshlrev_b64 v[128:129], 12, v[128:129]
	v_lshl_add_u64 v[128:129], s[42:43], 0, v[128:129]
	v_lshl_add_u64 v[132:133], v[128:129], 0, v[206:207]
	global_load_dwordx4 v[144:147], v[132:133], off offset:16
	global_load_dwordx4 v[148:151], v[132:133], off
	global_load_dwordx4 v[128:131], v[132:133], off offset:528
	s_nop 0
	global_load_dwordx4 v[132:135], v[132:133], off offset:512
	v_ashrrev_i32_e32 v209, 31, v208
	v_lshlrev_b64 v[224:225], 11, v[208:209]
	v_lshl_add_u64 v[224:225], s[14:15], 0, v[224:225]
	v_lshl_add_u64 v[224:225], v[204:205], 1, v[224:225]
	s_waitcnt vmcnt(0)
; __device__ __forceinline__ float quad_sum(float s) { s += __shfl_xor(s, 16); s += __shfl_xor(s, 32); return s; }
; __device__ __forceinline__ float sq4(const f32x4 a) { return (a[0] * a[0] + a[1] * a[1]) + (a[2] * a[2] + a[3] * a[3]); }
; __device__ __forceinline__ u32x4 pack8(const f32x4 a, const f32x4 b) { u32x4 w; w.x = cvt_pk_bf16(a[0], a[1]); w.y = cvt_pk_bf16(a[2], a[3]); w.z = cvt_pk_bf16(b[0], b[1]); w.w = cvt_pk_bf16(b[2], b[3]); return w; }
;     __device__ __forceinline__ void operator()(const f32x4 (&acc)[2][2][4][2], const Unit& u, int wr, int wc, int fr, int fq) const {
;     ...
;             for (int m = 0; m < 4; ++m) {
;                 const int row = u.pm * BM + ai * HALF + wr * 64 + m * 16 + fr;
;                 float ss = 0.f;
; #pragma unroll
;                 for (int bj = 0; bj < 2; ++bj) {
;                     const int c = col0 + bj * HALF;
;                     const f32x4 y0 = bv[m][bj][0] + acc[ai][bj][m][0], y1 = bv[m][bj][1] + acc[ai][bj][m][1];
;                     float* d = out + (size_t)row * 1024 + c; *(f32x4*)d = y0; *(f32x4*)(d + 4) = y1;
;                     *(u32x4*)(AB + (size_t)row * 1024 + c) = pack8(y0, y1);
;                     ss += sq4(y0) + sq4(y1);
;                 }
;                 ss = quad_sum(ss);
;                 if (fq == 0) PS[(size_t)row * 16 + u.pn * 4 + wc] = ss;
	v_pk_add_f32 v[120:121], v[120:121], v[232:233]
	v_lshlrev_b64 v[232:233], 12, v[208:209]
	v_lshl_add_u64 v[232:233], s[74:75], 0, v[232:233]
	v_pk_add_f32 v[126:127], v[126:127], v[238:239]
	v_pk_add_f32 v[124:125], v[124:125], v[236:237]
	v_lshl_add_u64 v[236:237], v[232:233], 0, v[206:207]
	v_pk_add_f32 v[122:123], v[122:123], v[234:235]
	global_store_dwordx4 v[236:237], v[124:127], off
	global_store_dwordx4 v[236:237], v[120:123], off offset:16
	v_cvt_pk_bf16_f32 v232, v124, v125
	v_cvt_pk_bf16_f32 v233, v126, v127
	v_cvt_pk_bf16_f32 v234, v120, v121
	v_pk_add_f32 v[118:119], v[118:119], v[182:183]
	v_mul_f32_e32 v125, v125, v125
	v_mul_f32_e32 v121, v121, v121
	v_fmac_f32_e32 v125, v124, v124
	v_mul_f32_e32 v124, v127, v127
	v_fmac_f32_e32 v121, v120, v120
	v_mul_f32_e32 v120, v123, v123
	v_fmac_f32_e32 v124, v126, v126
	v_fmac_f32_e32 v120, v122, v122
	v_add_f32_e32 v124, v125, v124
	v_add_f32_e32 v120, v121, v120
	v_pk_add_f32 v[116:117], v[116:117], v[180:181]
	v_pk_add_f32 v[112:113], v[112:113], v[176:177]
	v_cvt_pk_bf16_f32 v235, v122, v123
	global_store_dwordx4 v[224:225], v[232:235], off
	v_add_f32_e32 v124, v124, v120
	v_pk_add_f32 v[114:115], v[114:115], v[178:179]
	global_store_dwordx4 v[236:237], v[116:119], off offset:512
	global_store_dwordx4 v[236:237], v[112:115], off offset:528
	v_cvt_pk_bf16_f32 v120, v116, v117
	v_cvt_pk_bf16_f32 v121, v118, v119
	v_cvt_pk_bf16_f32 v122, v112, v113
	v_cvt_pk_bf16_f32 v123, v114, v115
	s_nop 0
	v_mul_f32_e32 v117, v117, v117
	v_mul_f32_e32 v113, v113, v113
	v_fmac_f32_e32 v113, v112, v112
	v_mul_f32_e32 v112, v115, v115
	v_fmac_f32_e32 v117, v116, v116
	v_mul_f32_e32 v116, v119, v119
	v_fmac_f32_e32 v112, v114, v114
	v_and_b32_e32 v114, 64, v222
	v_fmac_f32_e32 v116, v118, v118
	v_add_f32_e32 v112, v113, v112
	v_xor_b32_e32 v113, 16, v222
	v_add_u32_e32 v114, 64, v114
	v_add_f32_e32 v116, v117, v116
	v_cmp_lt_i32_e64 s[0:1], v113, v114
	v_add_f32_e32 v112, v116, v112
	v_add_f32_e32 v112, v124, v112
	v_cndmask_b32_e64 v113, v222, v113, s[0:1]
	v_lshlrev_b32_e32 v176, 2, v113
	ds_bpermute_b32 v113, v176, v112
	global_store_dwordx4 v[224:225], v[120:123], off offset:256
	s_waitcnt lgkmcnt(0)
	v_add_f32_e32 v112, v112, v113
	v_xor_b32_e32 v113, 32, v222
	v_cmp_lt_i32_e64 s[0:1], v113, v114
	s_nop 1
	v_cndmask_b32_e64 v113, v222, v113, s[0:1]
	v_lshlrev_b32_e32 v177, 2, v113
	ds_bpermute_b32 v113, v177, v112
	s_and_saveexec_b64 s[0:1], s[36:37]
	v_readlane_b32 s58, v255, 9
	v_readlane_b32 s59, v255, 10
	v_readlane_b32 s92, v255, 11
	v_readlane_b32 s93, v255, 16
	s_cbranch_execz .LBB0_223
	v_lshlrev_b64 v[114:115], 6, v[208:209]
	v_lshl_add_u64 v[114:115], s[40:41], 0, v[114:115]
	s_waitcnt lgkmcnt(0)
	v_add_f32_e32 v112, v112, v113
	global_store_dword v[114:115], v112, off

; #define PG8_STAGE(bufoff, gbase, voff) do { _Pragma("unroll") for (int _i = 0; _i < 2; ++_i) \
;         __builtin_amdgcn_global_load_lds((const unsigned*)((const char*)(gbase) + (voff)[_i]), (PG8_LAS unsigned*)(lds + (bufoff) + ldsw + _i * 8192), 16, 0, 0); } while (0)
; #define PG8_LDA(dst, b, h) do { _Pragma("unroll") for (int m = 0; m < 4; ++m) _Pragma("unroll") for (int k = 0; k < 2; ++k) dst[m][k] = *(const PG8_LAS bf16x8*)(lds + PG8_SA(b, h) + aoff + m * 2048 + k * 1024); } while (0)
; #define PG8_LDB(dst, b, h) do { _Pragma("unroll") for (int n = 0; n < 2; ++n) _Pragma("unroll") for (int k = 0; k < 2; ++k) dst[n][k] = *(const PG8_LAS bf16x8*)(lds + PG8_SB(b, h) + boff + n * 2048 + k * 1024); } while (0)
; #define PG8_MMA(ai, bj, At, Bt) do { __builtin_amdgcn_s_setprio(1); _Pragma("unroll") for (int m = 0; m < 4; ++m) _Pragma("unroll") for (int n = 0; n < 2; ++n) _Pragma("unroll") for (int k = 0; k < 2; ++k) \
;         acc[ai][bj][m][n] = __builtin_amdgcn_mfma_f32_16x16x32_bf16(Bt[n][k], At[m][k], acc[ai][bj][m][n], 0, 0, 0); __builtin_amdgcn_s_setprio(0); } while (0)
; #define PG8_WAIT_V(n) asm volatile("s_waitcnt vmcnt(" #n ")" ::: "memory")
; #define PG8_WAIT_L(n) asm volatile("s_waitcnt lgkmcnt(" #n ")" ::: "memory")
; #define PG8_BAR __builtin_amdgcn_s_barrier()
; #define PG8_SCHED __builtin_amdgcn_sched_barrier(0)
; template <class Epi, class Sched, bool ALIGN_EPI = false, bool SP2 = false>
; __device__ __forceinline__ void gemm_phase(PG8_LAS unsigned char* lds, const Gemm g, const Sched& S, const Epi& E) {
;     ...
;             const bool last = (t == nt - 2);
;             const char* a1 = cA + (size_t)(t + 1) * kstep;
;             const char* a2 = last ? nA : cA + (size_t)(t + 2) * kstep; const char* b2 = last ? nB : cB + (size_t)(t + 2) * kstep;
;             const char* a3 = a2 + kstep; const char* b3 = b2 + kstep;
;             if (last && has_next) S.a_ready(nxt);
;             if constexpr (SP2) {
;             PG8_LDB(B0, 0, 0); PG8_LDB(B1, 0, 1); PG8_SCHED; PG8_LDA(At, 0, 0); PG8_STAGE(PG8_SA(1, 1), a1 + hstep, voffA);
;             PG8_WAIT_V(8); PG8_WAIT_L(0); PG8_BAR; PG8_MMA(0, 0, At, B0); PG8_MMA(0, 1, At, B1); PG8_BAR; PG8_SCHED;
;             PG8_LDA(At, 0, 1); PG8_STAGE(PG8_SB(0, 0), b2, voffB); PG8_STAGE(PG8_SB(0, 1), b2 + hstep, voffB); PG8_STAGE(PG8_SA(0, 0), a2, voffA);
.LBB0_461:
	s_add_u32 s0, s22, 0x100
	s_addc_u32 s1, s23, 0
	s_cmp_eq_u32 s50, 40
	s_cselect_b32 s27, s19, s1
	s_cselect_b32 s26, s18, s0
	s_cselect_b32 s25, s21, s5
	s_cselect_b32 s24, s20, s4
	s_add_i32 s6, 0, 0x10000
	s_add_i32 s51, 0, 0x14000
	v_add_u32_e32 v140, s6, v228
	v_add_u32_e32 v156, s51, v228
	ds_read_b128 v[128:131], v140
	ds_read_b128 v[132:135], v140 offset:1024
	ds_read_b128 v[136:139], v140 offset:2048
	ds_read_b128 v[140:143], v140 offset:3072
	ds_read_b128 v[144:147], v156
	ds_read_b128 v[148:151], v156 offset:1024
	ds_read_b128 v[152:155], v156 offset:2048
	ds_read_b128 v[156:159], v156 offset:3072
	s_add_u32 s98, s22, 0xb0080
	s_addc_u32 s99, s23, 0
	s_add_i32 m0, s30, 0xc000
	ds_read_b128 v[160:163], v230
	ds_read_b128 v[164:167], v230 offset:1024
	ds_read_b128 v[168:171], v230 offset:2048
	ds_read_b128 v[172:175], v230 offset:3072
	ds_read_b128 v[176:179], v230 offset:4096
	ds_read_b128 v[180:183], v230 offset:5120
	ds_read_b128 v[204:207], v230 offset:6144
	ds_read_b128 v[208:211], v230 offset:7168
	ds_read_b128 v[212:215], v249
	ds_read_b128 v[232:235], v249 offset:1024
	global_load_lds_dwordx4 v198, s[98:99]
	s_add_i32 m0, s30, 0xe000
	s_nop 0
	global_load_lds_dwordx4 v196, s[98:99]
	s_waitcnt vmcnt(9)
	s_waitcnt lgkmcnt(0)
	s_barrier
	s_setprio 1
	s_waitcnt lgkmcnt(0)
	v_mfma_f32_16x16x32_bf16 v[124:127], v[128:131], v[160:163], v[124:127]
	v_mfma_f32_16x16x32_bf16 v[120:123], v[136:139], v[160:163], v[120:123]
	v_mfma_f32_16x16x32_bf16 v[108:111], v[128:131], v[168:171], v[108:111]
	v_mfma_f32_16x16x32_bf16 v[104:107], v[136:139], v[168:171], v[104:107]
	v_mfma_f32_16x16x32_bf16 v[92:95], v[128:131], v[176:179], v[92:95]
	v_mfma_f32_16x16x32_bf16 v[88:91], v[136:139], v[176:179], v[88:91]
	v_mfma_f32_16x16x32_bf16 v[76:79], v[128:131], v[204:207], v[76:79]
	v_mfma_f32_16x16x32_bf16 v[72:75], v[136:139], v[204:207], v[72:75]
	v_mfma_f32_16x16x32_bf16 v[124:127], v[132:135], v[164:167], v[124:127]
	v_mfma_f32_16x16x32_bf16 v[120:123], v[140:143], v[164:167], v[120:123]
	v_mfma_f32_16x16x32_bf16 v[108:111], v[132:135], v[172:175], v[108:111]
	v_mfma_f32_16x16x32_bf16 v[104:107], v[140:143], v[172:175], v[104:107]
	v_mfma_f32_16x16x32_bf16 v[92:95], v[132:135], v[180:183], v[92:95]
	v_mfma_f32_16x16x32_bf16 v[88:91], v[140:143], v[180:183], v[88:91]
	v_mfma_f32_16x16x32_bf16 v[76:79], v[132:135], v[208:211], v[76:79]
	v_mfma_f32_16x16x32_bf16 v[72:75], v[140:143], v[208:211], v[72:75]
	s_setprio 0
	s_setprio 1
	v_mfma_f32_16x16x32_bf16 v[116:119], v[144:147], v[160:163], v[116:119]
	v_mfma_f32_16x16x32_bf16 v[112:115], v[152:155], v[160:163], v[112:115]
	v_mfma_f32_16x16x32_bf16 v[100:103], v[144:147], v[168:171], v[100:103]
	v_mfma_f32_16x16x32_bf16 v[96:99], v[152:155], v[168:171], v[96:99]
	v_mfma_f32_16x16x32_bf16 v[84:87], v[144:147], v[176:179], v[84:87]
	v_mfma_f32_16x16x32_bf16 v[80:83], v[152:155], v[176:179], v[80:83]
	v_mfma_f32_16x16x32_bf16 v[68:71], v[144:147], v[204:207], v[68:71]
	v_mfma_f32_16x16x32_bf16 v[64:67], v[152:155], v[204:207], v[64:67]
	v_mfma_f32_16x16x32_bf16 v[116:119], v[148:151], v[164:167], v[116:119]
	v_mfma_f32_16x16x32_bf16 v[112:115], v[156:159], v[164:167], v[112:115]
	v_mfma_f32_16x16x32_bf16 v[100:103], v[148:151], v[172:175], v[100:103]
	v_mfma_f32_16x16x32_bf16 v[96:99], v[156:159], v[172:175], v[96:99]
	v_mfma_f32_16x16x32_bf16 v[84:87], v[148:151], v[180:183], v[84:87]
	v_mfma_f32_16x16x32_bf16 v[80:83], v[156:159], v[180:183], v[80:83]
	v_mfma_f32_16x16x32_bf16 v[68:71], v[148:151], v[208:211], v[68:71]
	v_mfma_f32_16x16x32_bf16 v[64:67], v[156:159], v[208:211], v[64:67]
	v_mfma_f32_16x16x32_bf16 v[236:239], v[128:131], v[212:215], v[236:239]
	v_mfma_f32_16x16x32_bf16 v[240:243], v[136:139], v[212:215], v[240:243]
	v_mfma_f32_16x16x32_bf16 v[244:247], v[144:147], v[212:215], v[244:247]
	v_mfma_f32_16x16x32_bf16 v[200:203], v[152:155], v[212:215], v[200:203]
	v_mfma_f32_16x16x32_bf16 v[236:239], v[132:135], v[232:235], v[236:239]
	v_mfma_f32_16x16x32_bf16 v[240:243], v[140:143], v[232:235], v[240:243]
	v_mfma_f32_16x16x32_bf16 v[244:247], v[148:151], v[232:235], v[244:247]
	v_mfma_f32_16x16x32_bf16 v[200:203], v[156:159], v[232:235], v[200:203]
	s_setprio 0
	s_barrier
	s_add_i32 s6, s6, s29
	s_mov_b32 m0, s6
	ds_read_b128 v[160:163], v230 offset:16384
	ds_read_b128 v[164:167], v230 offset:17408
	ds_read_b128 v[168:171], v230 offset:18432
	ds_read_b128 v[172:175], v230 offset:19456
	ds_read_b128 v[176:179], v230 offset:20480
	ds_read_b128 v[180:183], v230 offset:21504
	ds_read_b128 v[204:207], v230 offset:22528
	ds_read_b128 v[208:211], v230 offset:23552
	global_load_lds_dwordx4 v184, s[24:25]
	s_add_i32 m0, s6, 0x2000
	s_add_u32 s22, s24, 0xb0000
	s_addc_u32 s23, s25, 0
	s_add_i32 s6, s51, s29
	global_load_lds_dwordx4 v194, s[24:25]
	s_mov_b32 m0, s6
	s_nop 0
	global_load_lds_dwordx4 v184, s[22:23]
	s_add_i32 m0, s6, 0x2000
	s_nop 0
	global_load_lds_dwordx4 v194, s[22:23]
	s_mov_b32 m0, s30
	s_nop 0
	global_load_lds_dwordx4 v198, s[26:27]
	s_mov_b32 m0, s31
	s_nop 0
	global_load_lds_dwordx4 v196, s[26:27]
	s_and_b32 m0, s30, 0xc00
	s_add_i32 m0, m0, 0x20800
	s_nop 0
	global_load_lds_dwordx4 v248, s[26:27]
	s_nop 0
	s_waitcnt vmcnt(9)
	s_waitcnt lgkmcnt(0)
	s_barrier
; #define PG8_STAGE(bufoff, gbase, voff) do { _Pragma("unroll") for (int _i = 0; _i < 2; ++_i) \
;         __builtin_amdgcn_global_load_lds((const unsigned*)((const char*)(gbase) + (voff)[_i]), (PG8_LAS unsigned*)(lds + (bufoff) + ldsw + _i * 8192), 16, 0, 0); } while (0)
; #define PG8_LDA(dst, b, h) do { _Pragma("unroll") for (int m = 0; m < 4; ++m) _Pragma("unroll") for (int k = 0; k < 2; ++k) dst[m][k] = *(const PG8_LAS bf16x8*)(lds + PG8_SA(b, h) + aoff + m * 2048 + k * 1024); } while (0)
; #define PG8_LDB(dst, b, h) do { _Pragma("unroll") for (int n = 0; n < 2; ++n) _Pragma("unroll") for (int k = 0; k < 2; ++k) dst[n][k] = *(const PG8_LAS bf16x8*)(lds + PG8_SB(b, h) + boff + n * 2048 + k * 1024); } while (0)
; #define PG8_MMA(ai, bj, At, Bt) do { __builtin_amdgcn_s_setprio(1); _Pragma("unroll") for (int m = 0; m < 4; ++m) _Pragma("unroll") for (int n = 0; n < 2; ++n) _Pragma("unroll") for (int k = 0; k < 2; ++k) \
;         acc[ai][bj][m][n] = __builtin_amdgcn_mfma_f32_16x16x32_bf16(Bt[n][k], At[m][k], acc[ai][bj][m][n], 0, 0, 0); __builtin_amdgcn_s_setprio(0); } while (0)
; #define PG8_WAIT_V(n) asm volatile("s_waitcnt vmcnt(" #n ")" ::: "memory")
; #define PG8_WAIT_L(n) asm volatile("s_waitcnt lgkmcnt(" #n ")" ::: "memory")
; #define PG8_BAR __builtin_amdgcn_s_barrier()
; #define PG8_SCHED __builtin_amdgcn_sched_barrier(0)
; template <class Epi, class Sched, bool ALIGN_EPI = false, bool SP2 = false>
; __device__ __forceinline__ void gemm_phase(PG8_LAS unsigned char* lds, const Gemm g, const Sched& S, const Epi& E) {
;     ...
;             PG8_WAIT_V(8); PG8_WAIT_L(0); PG8_BAR; PG8_MMA(1, 0, At, B0); PG8_MMA(1, 1, At, B1); PG8_BAR; PG8_SCHED;
;             PG8_LDB(B0, 1, 0); PG8_LDB(B1, 1, 1); PG8_SCHED; PG8_LDA(At, 1, 0); PG8_STAGE(PG8_SA(0, 1), a2 + hstep, voffA);
;             PG8_WAIT_V(8); PG8_WAIT_L(0); PG8_BAR; PG8_MMA(0, 0, At, B0); PG8_MMA(0, 1, At, B1); PG8_BAR; PG8_SCHED;
	s_setprio 1
	s_waitcnt lgkmcnt(0)
	v_mfma_f32_16x16x32_bf16 v[60:63], v[128:131], v[160:163], v[60:63]
	v_mfma_f32_16x16x32_bf16 v[56:59], v[136:139], v[160:163], v[56:59]
	v_mfma_f32_16x16x32_bf16 v[44:47], v[128:131], v[168:171], v[44:47]
	v_mfma_f32_16x16x32_bf16 v[40:43], v[136:139], v[168:171], v[40:43]
	v_mfma_f32_16x16x32_bf16 v[28:31], v[128:131], v[176:179], v[28:31]
	v_mfma_f32_16x16x32_bf16 v[24:27], v[136:139], v[176:179], v[24:27]
	v_mfma_f32_16x16x32_bf16 v[12:15], v[128:131], v[204:207], v[12:15]
	v_mfma_f32_16x16x32_bf16 v[8:11], v[136:139], v[204:207], v[8:11]
	v_mfma_f32_16x16x32_bf16 v[60:63], v[132:135], v[164:167], v[60:63]
	v_mfma_f32_16x16x32_bf16 v[56:59], v[140:143], v[164:167], v[56:59]
	v_mfma_f32_16x16x32_bf16 v[44:47], v[132:135], v[172:175], v[44:47]
	v_mfma_f32_16x16x32_bf16 v[40:43], v[140:143], v[172:175], v[40:43]
	v_mfma_f32_16x16x32_bf16 v[28:31], v[132:135], v[180:183], v[28:31]
	v_mfma_f32_16x16x32_bf16 v[24:27], v[140:143], v[180:183], v[24:27]
	v_mfma_f32_16x16x32_bf16 v[12:15], v[132:135], v[208:211], v[12:15]
	v_mfma_f32_16x16x32_bf16 v[8:11], v[140:143], v[208:211], v[8:11]
	s_setprio 0
	s_setprio 1
	v_mfma_f32_16x16x32_bf16 v[52:55], v[144:147], v[160:163], v[52:55]
	v_mfma_f32_16x16x32_bf16 v[48:51], v[152:155], v[160:163], v[48:51]
	v_mfma_f32_16x16x32_bf16 v[36:39], v[144:147], v[168:171], v[36:39]
	v_mfma_f32_16x16x32_bf16 v[32:35], v[152:155], v[168:171], v[32:35]
	v_mfma_f32_16x16x32_bf16 v[20:23], v[144:147], v[176:179], v[20:23]
	v_mfma_f32_16x16x32_bf16 v[16:19], v[152:155], v[176:179], v[16:19]
	v_mfma_f32_16x16x32_bf16 v[4:7], v[144:147], v[204:207], v[4:7]
	v_mfma_f32_16x16x32_bf16 v[0:3], v[152:155], v[204:207], v[0:3]
	v_mfma_f32_16x16x32_bf16 v[52:55], v[148:151], v[164:167], v[52:55]
	v_mfma_f32_16x16x32_bf16 v[48:51], v[156:159], v[164:167], v[48:51]
	v_mfma_f32_16x16x32_bf16 v[36:39], v[148:151], v[172:175], v[36:39]
	v_mfma_f32_16x16x32_bf16 v[32:35], v[156:159], v[172:175], v[32:35]
	v_mfma_f32_16x16x32_bf16 v[20:23], v[148:151], v[180:183], v[20:23]
	v_mfma_f32_16x16x32_bf16 v[16:19], v[156:159], v[180:183], v[16:19]
	v_mfma_f32_16x16x32_bf16 v[4:7], v[148:151], v[208:211], v[4:7]
	v_mfma_f32_16x16x32_bf16 v[0:3], v[156:159], v[208:211], v[0:3]
	s_setprio 0
	s_barrier
	s_add_i32 s6, 0, 0x18000
	s_add_i32 s51, 0, 0x1c000
	v_add_u32_e32 v140, s6, v228
	v_add_u32_e32 v156, s51, v228
	ds_read_b128 v[128:131], v140
	ds_read_b128 v[132:135], v140 offset:1024
	ds_read_b128 v[136:139], v140 offset:2048
	ds_read_b128 v[140:143], v140 offset:3072
	ds_read_b128 v[144:147], v156
	ds_read_b128 v[148:151], v156 offset:1024
	ds_read_b128 v[152:155], v156 offset:2048
	ds_read_b128 v[156:159], v156 offset:3072
	s_add_u32 s22, s26, 0xb0000
	s_addc_u32 s23, s27, 0
	s_mov_b32 m0, s34
	ds_read_b128 v[160:163], v230 offset:32768
	ds_read_b128 v[164:167], v230 offset:33792
	ds_read_b128 v[168:171], v230 offset:34816
	ds_read_b128 v[172:175], v230 offset:35840
	ds_read_b128 v[176:179], v230 offset:36864
	ds_read_b128 v[180:183], v230 offset:37888
	ds_read_b128 v[204:207], v230 offset:38912
	ds_read_b128 v[208:211], v230 offset:39936
	ds_read_b128 v[212:215], v249 offset:4096
	ds_read_b128 v[232:235], v249 offset:5120
	global_load_lds_dwordx4 v198, s[22:23]
	s_mov_b32 m0, s40
	s_nop 0
	global_load_lds_dwordx4 v196, s[22:23]
	s_nop 0
	s_waitcnt vmcnt(9)
	s_waitcnt lgkmcnt(0)
	s_barrier
	s_setprio 1
	s_waitcnt lgkmcnt(0)
	v_mfma_f32_16x16x32_bf16 v[124:127], v[128:131], v[160:163], v[124:127]
	v_mfma_f32_16x16x32_bf16 v[120:123], v[136:139], v[160:163], v[120:123]
	v_mfma_f32_16x16x32_bf16 v[108:111], v[128:131], v[168:171], v[108:111]
	v_mfma_f32_16x16x32_bf16 v[104:107], v[136:139], v[168:171], v[104:107]
	v_mfma_f32_16x16x32_bf16 v[92:95], v[128:131], v[176:179], v[92:95]
	v_mfma_f32_16x16x32_bf16 v[88:91], v[136:139], v[176:179], v[88:91]
	v_mfma_f32_16x16x32_bf16 v[76:79], v[128:131], v[204:207], v[76:79]
	v_mfma_f32_16x16x32_bf16 v[72:75], v[136:139], v[204:207], v[72:75]
	v_mfma_f32_16x16x32_bf16 v[124:127], v[132:135], v[164:167], v[124:127]
	v_mfma_f32_16x16x32_bf16 v[120:123], v[140:143], v[164:167], v[120:123]
	v_mfma_f32_16x16x32_bf16 v[108:111], v[132:135], v[172:175], v[108:111]
	v_mfma_f32_16x16x32_bf16 v[104:107], v[140:143], v[172:175], v[104:107]
	v_mfma_f32_16x16x32_bf16 v[92:95], v[132:135], v[180:183], v[92:95]
	v_mfma_f32_16x16x32_bf16 v[88:91], v[140:143], v[180:183], v[88:91]
	v_mfma_f32_16x16x32_bf16 v[76:79], v[132:135], v[208:211], v[76:79]
	v_mfma_f32_16x16x32_bf16 v[72:75], v[140:143], v[208:211], v[72:75]
	s_setprio 0
	s_setprio 1
	v_mfma_f32_16x16x32_bf16 v[116:119], v[144:147], v[160:163], v[116:119]
	v_mfma_f32_16x16x32_bf16 v[112:115], v[152:155], v[160:163], v[112:115]
	v_mfma_f32_16x16x32_bf16 v[100:103], v[144:147], v[168:171], v[100:103]
	v_mfma_f32_16x16x32_bf16 v[96:99], v[152:155], v[168:171], v[96:99]
	v_mfma_f32_16x16x32_bf16 v[84:87], v[144:147], v[176:179], v[84:87]
	v_mfma_f32_16x16x32_bf16 v[80:83], v[152:155], v[176:179], v[80:83]
	v_mfma_f32_16x16x32_bf16 v[68:71], v[144:147], v[204:207], v[68:71]
	v_mfma_f32_16x16x32_bf16 v[64:67], v[152:155], v[204:207], v[64:67]
	v_mfma_f32_16x16x32_bf16 v[116:119], v[148:151], v[164:167], v[116:119]
	v_mfma_f32_16x16x32_bf16 v[112:115], v[156:159], v[164:167], v[112:115]
	v_mfma_f32_16x16x32_bf16 v[100:103], v[148:151], v[172:175], v[100:103]
	v_mfma_f32_16x16x32_bf16 v[96:99], v[156:159], v[172:175], v[96:99]
	v_mfma_f32_16x16x32_bf16 v[84:87], v[148:151], v[180:183], v[84:87]
	v_mfma_f32_16x16x32_bf16 v[80:83], v[156:159], v[180:183], v[80:83]
	v_mfma_f32_16x16x32_bf16 v[68:71], v[148:151], v[208:211], v[68:71]
	v_mfma_f32_16x16x32_bf16 v[64:67], v[156:159], v[208:211], v[64:67]
	v_mfma_f32_16x16x32_bf16 v[236:239], v[128:131], v[212:215], v[236:239]
	v_mfma_f32_16x16x32_bf16 v[240:243], v[136:139], v[212:215], v[240:243]
	v_mfma_f32_16x16x32_bf16 v[244:247], v[144:147], v[212:215], v[244:247]
	v_mfma_f32_16x16x32_bf16 v[200:203], v[152:155], v[212:215], v[200:203]
	v_mfma_f32_16x16x32_bf16 v[236:239], v[132:135], v[232:235], v[236:239]
	v_mfma_f32_16x16x32_bf16 v[240:243], v[140:143], v[232:235], v[240:243]
	v_mfma_f32_16x16x32_bf16 v[244:247], v[148:151], v[232:235], v[244:247]
	v_mfma_f32_16x16x32_bf16 v[200:203], v[156:159], v[232:235], v[200:203]
	s_setprio 0
	s_barrier
; #define PG8_STAGE(bufoff, gbase, voff) do { _Pragma("unroll") for (int _i = 0; _i < 2; ++_i) \
;         __builtin_amdgcn_global_load_lds((const unsigned*)((const char*)(gbase) + (voff)[_i]), (PG8_LAS unsigned*)(lds + (bufoff) + ldsw + _i * 8192), 16, 0, 0); } while (0)
; #define PG8_LDA(dst, b, h) do { _Pragma("unroll") for (int m = 0; m < 4; ++m) _Pragma("unroll") for (int k = 0; k < 2; ++k) dst[m][k] = *(const PG8_LAS bf16x8*)(lds + PG8_SA(b, h) + aoff + m * 2048 + k * 1024); } while (0)
; #define PG8_MMA(ai, bj, At, Bt) do { __builtin_amdgcn_s_setprio(1); _Pragma("unroll") for (int m = 0; m < 4; ++m) _Pragma("unroll") for (int n = 0; n < 2; ++n) _Pragma("unroll") for (int k = 0; k < 2; ++k) \
;         acc[ai][bj][m][n] = __builtin_amdgcn_mfma_f32_16x16x32_bf16(Bt[n][k], At[m][k], acc[ai][bj][m][n], 0, 0, 0); __builtin_amdgcn_s_setprio(0); } while (0)
; #define PG8_WAIT_V(n) asm volatile("s_waitcnt vmcnt(" #n ")" ::: "memory")
; #define PG8_WAIT_L(n) asm volatile("s_waitcnt lgkmcnt(" #n ")" ::: "memory")
; #define PG8_BAR __builtin_amdgcn_s_barrier()
; #define PG8_SCHED __builtin_amdgcn_sched_barrier(0)
; template <class Epi, class Sched, bool ALIGN_EPI = false, bool SP2 = false>
; __device__ __forceinline__ void gemm_phase(PG8_LAS unsigned char* lds, const Gemm g, const Sched& S, const Epi& E) {
;     ...
;             PG8_LDA(At, 1, 1); PG8_STAGE(PG8_SB(1, 0), b3, voffB); PG8_STAGE(PG8_SB(1, 1), b3 + hstep, voffB); PG8_STAGE(PG8_SA(1, 0), a3, voffA);
;             PG8_WAIT_V(8); PG8_WAIT_L(0); PG8_BAR; PG8_MMA(1, 0, At, B0); PG8_MMA(1, 1, At, B1); PG8_BAR; PG8_SCHED;
; __device__ __forceinline__ void small_gemm_res(LAS unsigned char* lds, const bf16* A, const bf16* Bt, int K, const float* base_s, float* out, bf16* AB, float* PS, int sm, int sn, int tid_in) {
;     ...
;     f32x4 bv[2][2];
; #pragma unroll
;     for (int m_ = 0; m_ < 2; ++m_)
; #pragma unroll
;         for (int n = 0; n < 2; ++n) bv[m_][n] = *(const f32x4*)(base_s + (size_t)(row0 + wr * 32 + m_ * 16 + fr - MP) * D + col0 + wc * 32 + n * 16 + 4 * fq);
	s_add_i32 s22, s6, s29
	s_add_u32 s98, s24, 0x80
	s_addc_u32 s99, s25, 0
	s_mov_b32 m0, s22
	ds_read_b128 v[160:163], v230 offset:49152
	ds_read_b128 v[164:167], v230 offset:50176
	ds_read_b128 v[168:171], v230 offset:51200
	ds_read_b128 v[172:175], v230 offset:52224
	ds_read_b128 v[176:179], v230 offset:53248
	ds_read_b128 v[180:183], v230 offset:54272
	ds_read_b128 v[204:207], v230 offset:55296
	ds_read_b128 v[208:211], v230 offset:56320
	global_load_lds_dwordx4 v184, s[98:99]
	s_add_i32 m0, s22, 0x2000
	s_add_u32 s100, s24, 0xb0080
	s_addc_u32 s101, s25, 0
	s_add_i32 s22, s51, s29
	global_load_lds_dwordx4 v194, s[98:99]
	s_mov_b32 m0, s22
	s_add_u32 s98, s26, 0x80
	s_addc_u32 s99, s27, 0
	global_load_lds_dwordx4 v184, s[100:101]
	s_add_i32 m0, s22, 0x2000
	s_nop 0
	global_load_lds_dwordx4 v194, s[100:101]
	s_mov_b32 m0, s41
	s_nop 0
	global_load_lds_dwordx4 v198, s[98:99]
	s_mov_b32 m0, s42
	s_nop 0
	global_load_lds_dwordx4 v196, s[98:99]
	s_and_b32 m0, s30, 0xc00
	s_add_i32 m0, m0, 0x21800
	s_nop 0
	global_load_lds_dwordx4 v248, s[98:99]
	s_waitcnt vmcnt(9)
	s_waitcnt lgkmcnt(0)
	s_barrier
	s_setprio 1
	s_waitcnt lgkmcnt(0)
	v_mfma_f32_16x16x32_bf16 v[60:63], v[128:131], v[160:163], v[60:63]
	v_mfma_f32_16x16x32_bf16 v[56:59], v[136:139], v[160:163], v[56:59]
	v_mfma_f32_16x16x32_bf16 v[44:47], v[128:131], v[168:171], v[44:47]
	v_mfma_f32_16x16x32_bf16 v[40:43], v[136:139], v[168:171], v[40:43]
	v_mfma_f32_16x16x32_bf16 v[28:31], v[128:131], v[176:179], v[28:31]
	v_mfma_f32_16x16x32_bf16 v[24:27], v[136:139], v[176:179], v[24:27]
	v_mfma_f32_16x16x32_bf16 v[12:15], v[128:131], v[204:207], v[12:15]
	v_mfma_f32_16x16x32_bf16 v[8:11], v[136:139], v[204:207], v[8:11]
	v_mfma_f32_16x16x32_bf16 v[60:63], v[132:135], v[164:167], v[60:63]
	v_mfma_f32_16x16x32_bf16 v[56:59], v[140:143], v[164:167], v[56:59]
	v_mfma_f32_16x16x32_bf16 v[44:47], v[132:135], v[172:175], v[44:47]
	v_mfma_f32_16x16x32_bf16 v[40:43], v[140:143], v[172:175], v[40:43]
	v_mfma_f32_16x16x32_bf16 v[28:31], v[132:135], v[180:183], v[28:31]
	v_mfma_f32_16x16x32_bf16 v[24:27], v[140:143], v[180:183], v[24:27]
	v_mfma_f32_16x16x32_bf16 v[12:15], v[132:135], v[208:211], v[12:15]
	v_mfma_f32_16x16x32_bf16 v[8:11], v[140:143], v[208:211], v[8:11]
	s_setprio 0
	s_cmp_eq_u32 s50, 40
	s_cbranch_scc0 .Lxr_skip_461
	s_mul_i32 s98, s48, 0x120
	s_addk_i32 s98, 0x100
	v_and_b32_e32 v190, 15, v227
	v_lshrrev_b32_e32 v191, 6, v227
	v_lshl_add_u32 v190, v191, 4, v190
	v_add_u32_e32 v190, s98, v190
	v_mov_b32_e32 v191, 0
	v_lshlrev_b64 v[190:191], 12, v[190:191]
	v_lshl_add_u64 v[190:191], s[74:75], 0, v[190:191]
	v_lshl_or_b32 v217, s49, 8, v229
	v_lshlrev_b32_e32 v217, 2, v217
	v_add_co_u32_e32 v190, vcc, v190, v217
	s_nop 1
	v_addc_co_u32_e32 v191, vcc, 0, v191, vcc
	global_load_dwordx4 v[128:131], v[190:191], off
	global_load_dwordx4 v[132:135], v[190:191], off offset:16
	global_load_dwordx4 v[136:139], v[190:191], off offset:512
	global_load_dwordx4 v[140:143], v[190:191], off offset:528
.Lxr_skip_461:
	s_setprio 1
	v_mfma_f32_16x16x32_bf16 v[52:55], v[144:147], v[160:163], v[52:55]
	v_mfma_f32_16x16x32_bf16 v[48:51], v[152:155], v[160:163], v[48:51]
	v_mfma_f32_16x16x32_bf16 v[36:39], v[144:147], v[168:171], v[36:39]
	v_mfma_f32_16x16x32_bf16 v[32:35], v[152:155], v[168:171], v[32:35]
	v_mfma_f32_16x16x32_bf16 v[20:23], v[144:147], v[176:179], v[20:23]
	v_mfma_f32_16x16x32_bf16 v[16:19], v[152:155], v[176:179], v[16:19]
	v_mfma_f32_16x16x32_bf16 v[4:7], v[144:147], v[204:207], v[4:7]
	v_mfma_f32_16x16x32_bf16 v[0:3], v[152:155], v[204:207], v[0:3]
	v_mfma_f32_16x16x32_bf16 v[52:55], v[148:151], v[164:167], v[52:55]
	v_mfma_f32_16x16x32_bf16 v[48:51], v[156:159], v[164:167], v[48:51]
	v_mfma_f32_16x16x32_bf16 v[36:39], v[148:151], v[172:175], v[36:39]
	v_mfma_f32_16x16x32_bf16 v[32:35], v[156:159], v[172:175], v[32:35]
	v_mfma_f32_16x16x32_bf16 v[20:23], v[148:151], v[180:183], v[20:23]
	v_mfma_f32_16x16x32_bf16 v[16:19], v[156:159], v[180:183], v[16:19]
	v_mfma_f32_16x16x32_bf16 v[4:7], v[148:151], v[208:211], v[4:7]
	v_mfma_f32_16x16x32_bf16 v[0:3], v[156:159], v[208:211], v[0:3]
	s_setprio 0
	s_barrier
	s_add_i32 s50, s50, 2
	s_add_u32 s4, s4, 0x100
	s_addc_u32 s5, s5, 0
	s_cmp_gt_u32 s50, 41
	s_mov_b64 s[22:23], s[0:1]
	s_cbranch_scc0 .LBB0_461
	s_and_b64 vcc, exec, s[16:17]
	s_cbranch_vccz .LBB0_464
	s_barrier
.LBB0_464:
	s_mul_i32 s98, s48, 0x120
	v_and_b32_e32 v144, 15, v227
	v_lshrrev_b32_e32 v145, 6, v227
	v_lshl_add_u32 v144, v145, 4, v144
	v_add_u32_e32 v144, s98, v144
	v_add_u32_e32 v144, 0x100, v144
	v_mov_b32_e32 v145, 0
	v_lshl_or_b32 v146, s49, 8, v229
	v_mov_b32_e32 v147, 0
	v_lshlrev_b64 v[148:149], 12, v[144:145]
	v_lshl_add_u64 v[148:149], s[74:75], 0, v[148:149]
	v_lshl_add_u64 v[148:149], v[146:147], 2, v[148:149]


; __device__ __forceinline__ float quad_sum(float s) { s += __shfl_xor(s, 16); s += __shfl_xor(s, 32); return s; }
; __device__ __forceinline__ float sq4(const f32x4 a) { return (a[0] * a[0] + a[1] * a[1]) + (a[2] * a[2] + a[3] * a[3]); }
; __device__ __forceinline__ unsigned pk2(float lo, float hi) { return pg8::cvt_pk_bf16(lo, hi); }
;     __device__ __forceinline__ void operator()(const f32x4 (&acc)[2][2][4][2], const Unit& u, int wr, int wc, int fr, int fq) const {
;     ...
;                 const int row = u.pm * BM + ai * HALF + wr * 64 + m * 16 + fr;
;                 const float* bp = (u.pm < 64) ? base_p + (size_t)row * 1024 : base_s + (size_t)(row - E_MP) * 1024;
; #pragma unroll
;                 for (int bj = 0; bj < 2; ++bj) { bv[m][bj][0] = *(const f32x4*)(bp + col0 + bj * HALF); bv[m][bj][1] = *(const f32x4*)(bp + col0 + bj * HALF + 4); }
; __device__ __forceinline__ void small_gemm_res(LAS unsigned char* lds, const bf16* A, const bf16* Bt, int K, const float* base_s, float* out, bf16* AB, float* PS, int sm, int sn, int tid_in) {
;     ...
; #pragma unroll
;     for (int m_ = 0; m_ < 2; ++m_) {
;         const int rl = wr * 32 + m_ * 16 + fr, row = row0 + rl;
;         float ss = 0.f;
; #pragma unroll
;         for (int n = 0; n < 2; ++n) {
;             const int c = col0 + wc * 32 + n * 16 + 4 * fq;
;             const f32x4 y = bv[m_][n] + acc[m_][n];
;             *(f32x4*)(out + (size_t)row * D + c) = y;
;             *(v2u*)(AB + (size_t)row * D + c) = (v2u){pk2(y[0], y[1]), pk2(y[2], y[3])};
;             ss += pg8::sq4(y);
;         }
;         ss = pg8::quad_sum(ss);
;         if (fq == 0) red[rl * 4 + wc] = ss;
;     }
	v_lshlrev_b64 v[150:151], 11, v[144:145]
	v_lshl_add_u64 v[150:151], s[12:13], 0, v[150:151]
	v_lshl_add_u64 v[150:151], v[146:147], 1, v[150:151]
	s_lshl_b32 s98, s49, 4
	s_add_u32 s98, s44, s98
	s_addc_u32 s99, s45, 0
	v_lshlrev_b64 v[164:165], 6, v[144:145]
	v_lshl_add_u64 v[164:165], s[98:99], 0, v[164:165]
	v_xor_b32_e32 v162, 16, v222
	v_lshlrev_b32_e32 v162, 2, v162
	v_xor_b32_e32 v163, 32, v222
	v_lshlrev_b32_e32 v163, 2, v163
	s_waitcnt vmcnt(0)
	v_pk_add_f32 v[128:129], v[236:237], v[128:129]
	v_pk_add_f32 v[130:131], v[238:239], v[130:131]
	v_pk_add_f32 v[132:133], v[240:241], v[132:133]
	v_pk_add_f32 v[134:135], v[242:243], v[134:135]
	v_pk_add_f32 v[136:137], v[244:245], v[136:137]
	v_pk_add_f32 v[138:139], v[246:247], v[138:139]
	v_pk_add_f32 v[140:141], v[200:201], v[140:141]
	v_pk_add_f32 v[142:143], v[202:203], v[142:143]
	global_store_dwordx4 v[148:149], v[128:131], off
	global_store_dwordx4 v[148:149], v[132:135], off offset:16
	global_store_dwordx4 v[148:149], v[136:139], off offset:512
	global_store_dwordx4 v[148:149], v[140:143], off offset:528
	v_cvt_pk_bf16_f32 v152, v128, v129
	v_cvt_pk_bf16_f32 v153, v130, v131
	v_cvt_pk_bf16_f32 v154, v132, v133
	v_cvt_pk_bf16_f32 v155, v134, v135
	v_cvt_pk_bf16_f32 v156, v136, v137
	v_cvt_pk_bf16_f32 v157, v138, v139
	v_cvt_pk_bf16_f32 v158, v140, v141
	v_cvt_pk_bf16_f32 v159, v142, v143
	global_store_dwordx4 v[150:151], v[152:155], off
	global_store_dwordx4 v[150:151], v[156:159], off offset:256
	v_mul_f32_e32 v160, v128, v128
	v_fmac_f32_e32 v160, v129, v129
	v_fmac_f32_e32 v160, v130, v130
	v_fmac_f32_e32 v160, v131, v131
	v_fmac_f32_e32 v160, v132, v132
	v_fmac_f32_e32 v160, v133, v133
	v_fmac_f32_e32 v160, v134, v134
	v_fmac_f32_e32 v160, v135, v135
	v_fmac_f32_e32 v160, v136, v136
	v_fmac_f32_e32 v160, v137, v137
	v_fmac_f32_e32 v160, v138, v138
	v_fmac_f32_e32 v160, v139, v139
	v_fmac_f32_e32 v160, v140, v140
	v_fmac_f32_e32 v160, v141, v141
	v_fmac_f32_e32 v160, v142, v142
	v_fmac_f32_e32 v160, v143, v143
	ds_bpermute_b32 v161, v162, v160
	s_waitcnt lgkmcnt(0)
	v_add_f32_e32 v160, v160, v161
	ds_bpermute_b32 v161, v163, v160
	s_waitcnt lgkmcnt(0)
	v_add_f32_e32 v160, v160, v161
	s_and_saveexec_b64 s[98:99], s[36:37]
	global_store_dword v[164:165], v160, off
	s_or_b64 exec, exec, s[98:99]
	s_lshl_b32 s0, s49, 2
	s_ashr_i32 s1, s0, 31
	s_lshl_b64 s[0:1], s[0:1], 2
	s_add_u32 s22, s44, s0
	s_addc_u32 s23, s45, s1
	s_mul_i32 s98, s48, 0x120
	v_add_u32_e32 v208, s98, v227
	s_cmp_eq_u32 s48, s48
	s_cselect_b64 vcc, -1, 0
	v_add_u32_e32 v128, 0xffffc000, v208
	v_cndmask_b32_e32 v128, v128, v208, vcc
	v_lshl_or_b32 v204, s49, 8, v229
	s_and_b64 s[0:1], vcc, exec
	v_ashrrev_i32_e32 v129, 31, v128
	v_ashrrev_i32_e32 v205, 31, v204
	s_cselect_b32 s25, s75, s57
	s_cselect_b32 s24, s74, s56
	v_lshlrev_b64 v[128:129], 12, v[128:129]
	v_lshl_add_u64 v[128:129], s[24:25], 0, v[128:129]
	v_lshlrev_b64 v[206:207], 2, v[204:205]
	v_lshl_add_u64 v[128:129], v[128:129], 0, v[206:207]
	global_load_dwordx4 v[232:235], v[128:129], off offset:16
	global_load_dwordx4 v[236:239], v[128:129], off
	global_load_dwordx4 v[176:179], v[128:129], off offset:528
	global_load_dwordx4 v[180:183], v[128:129], off offset:512
	v_add_u32_e32 v214, 16, v208
	v_add_u32_e32 v128, 0xffffc010, v208
	v_cndmask_b32_e32 v128, v128, v214, vcc
	v_ashrrev_i32_e32 v129, 31, v128
	v_lshlrev_b64 v[128:129], 12, v[128:129]
	v_lshl_add_u64 v[128:129], s[24:25], 0, v[128:129]
	v_lshl_add_u64 v[128:129], v[128:129], 0, v[206:207]
	global_load_dwordx4 v[168:171], v[128:129], off offset:16
	global_load_dwordx4 v[172:175], v[128:129], off
	global_load_dwordx4 v[160:163], v[128:129], off offset:528
	global_load_dwordx4 v[164:167], v[128:129], off offset:512
	v_add_u32_e32 v212, 32, v208
	v_add_u32_e32 v128, 0xffffc020, v208
	v_cndmask_b32_e32 v128, v128, v212, vcc
	v_ashrrev_i32_e32 v129, 31, v128
	v_lshlrev_b64 v[128:129], 12, v[128:129]
	v_lshl_add_u64 v[128:129], s[24:25], 0, v[128:129]
	v_lshl_add_u64 v[128:129], v[128:129], 0, v[206:207]
	global_load_dwordx4 v[152:155], v[128:129], off offset:16
	global_load_dwordx4 v[156:159], v[128:129], off
	global_load_dwordx4 v[136:139], v[128:129], off offset:528
	global_load_dwordx4 v[140:143], v[128:129], off offset:512
	v_add_u32_e32 v210, 48, v208
	v_add_u32_e32 v128, 0xffffc030, v208
	v_cndmask_b32_e32 v128, v128, v210, vcc
	v_ashrrev_i32_e32 v129, 31, v128
	v_lshlrev_b64 v[128:129], 12, v[128:129]
	v_lshl_add_u64 v[128:129], s[24:25], 0, v[128:129]
	v_lshl_add_u64 v[132:133], v[128:129], 0, v[206:207]
	global_load_dwordx4 v[144:147], v[132:133], off offset:16
	global_load_dwordx4 v[148:151], v[132:133], off
	global_load_dwordx4 v[128:131], v[132:133], off offset:528
	s_nop 0
	global_load_dwordx4 v[132:135], v[132:133], off offset:512
	v_ashrrev_i32_e32 v209, 31, v208
	v_lshlrev_b64 v[224:225], 11, v[208:209]
	v_lshl_add_u64 v[224:225], s[12:13], 0, v[224:225]
	v_lshl_add_u64 v[224:225], v[204:205], 1, v[224:225]
	s_waitcnt vmcnt(0)
; __device__ __forceinline__ float quad_sum(float s) { s += __shfl_xor(s, 16); s += __shfl_xor(s, 32); return s; }
; __device__ __forceinline__ float sq4(const f32x4 a) { return (a[0] * a[0] + a[1] * a[1]) + (a[2] * a[2] + a[3] * a[3]); }
; __device__ __forceinline__ u32x4 pack8(const f32x4 a, const f32x4 b) { u32x4 w; w.x = cvt_pk_bf16(a[0], a[1]); w.y = cvt_pk_bf16(a[2], a[3]); w.z = cvt_pk_bf16(b[0], b[1]); w.w = cvt_pk_bf16(b[2], b[3]); return w; }
;     __device__ __forceinline__ void operator()(const f32x4 (&acc)[2][2][4][2], const Unit& u, int wr, int wc, int fr, int fq) const {
;     ...
;             for (int m = 0; m < 4; ++m) {
;                 const int row = u.pm * BM + ai * HALF + wr * 64 + m * 16 + fr;
;                 float ss = 0.f;
; #pragma unroll
;                 for (int bj = 0; bj < 2; ++bj) {
;                     const int c = col0 + bj * HALF;
;                     const f32x4 y0 = bv[m][bj][0] + acc[ai][bj][m][0], y1 = bv[m][bj][1] + acc[ai][bj][m][1];
;                     float* d = out + (size_t)row * 1024 + c; *(f32x4*)d = y0; *(f32x4*)(d + 4) = y1;
;                     *(u32x4*)(AB + (size_t)row * 1024 + c) = pack8(y0, y1);
;                     ss += sq4(y0) + sq4(y1);
;                 }
;                 ss = quad_sum(ss);
;                 if (fq == 0) PS[(size_t)row * 16 + u.pn * 4 + wc] = ss;
	v_pk_add_f32 v[120:121], v[120:121], v[232:233]
	v_lshlrev_b64 v[232:233], 12, v[208:209]
	v_lshl_add_u64 v[232:233], s[74:75], 0, v[232:233]
	v_pk_add_f32 v[126:127], v[126:127], v[238:239]
	v_pk_add_f32 v[124:125], v[124:125], v[236:237]
	v_lshl_add_u64 v[236:237], v[232:233], 0, v[206:207]
	v_pk_add_f32 v[122:123], v[122:123], v[234:235]
	global_store_dwordx4 v[236:237], v[124:127], off
	global_store_dwordx4 v[236:237], v[120:123], off offset:16
	v_cvt_pk_bf16_f32 v232, v124, v125
	v_cvt_pk_bf16_f32 v233, v126, v127
	v_cvt_pk_bf16_f32 v234, v120, v121
	v_pk_add_f32 v[118:119], v[118:119], v[182:183]
	v_mul_f32_e32 v125, v125, v125
	v_mul_f32_e32 v121, v121, v121
	v_fmac_f32_e32 v125, v124, v124
	v_mul_f32_e32 v124, v127, v127
	v_fmac_f32_e32 v121, v120, v120
	v_mul_f32_e32 v120, v123, v123
	v_fmac_f32_e32 v124, v126, v126
	v_fmac_f32_e32 v120, v122, v122
	v_add_f32_e32 v124, v125, v124
	v_add_f32_e32 v120, v121, v120
	v_pk_add_f32 v[116:117], v[116:117], v[180:181]
	v_pk_add_f32 v[112:113], v[112:113], v[176:177]
	v_cvt_pk_bf16_f32 v235, v122, v123
	global_store_dwordx4 v[224:225], v[232:235], off
	v_add_f32_e32 v124, v124, v120
	v_pk_add_f32 v[114:115], v[114:115], v[178:179]
	global_store_dwordx4 v[236:237], v[116:119], off offset:512
	global_store_dwordx4 v[236:237], v[112:115], off offset:528
	v_cvt_pk_bf16_f32 v120, v116, v117
	v_cvt_pk_bf16_f32 v121, v118, v119
	v_cvt_pk_bf16_f32 v122, v112, v113
	v_cvt_pk_bf16_f32 v123, v114, v115
	s_nop 0
	v_mul_f32_e32 v117, v117, v117
	v_mul_f32_e32 v113, v113, v113
	v_fmac_f32_e32 v113, v112, v112
	v_mul_f32_e32 v112, v115, v115
	v_fmac_f32_e32 v117, v116, v116
	v_mul_f32_e32 v116, v119, v119
	v_fmac_f32_e32 v112, v114, v114
	v_and_b32_e32 v114, 64, v222
	v_fmac_f32_e32 v116, v118, v118
	v_add_f32_e32 v112, v113, v112
	v_xor_b32_e32 v113, 16, v222
	v_add_u32_e32 v114, 64, v114
	v_add_f32_e32 v116, v117, v116
	v_cmp_lt_i32_e64 s[0:1], v113, v114
	v_add_f32_e32 v112, v116, v112
	v_add_f32_e32 v112, v124, v112
	v_cndmask_b32_e64 v113, v222, v113, s[0:1]
	v_lshlrev_b32_e32 v176, 2, v113
	ds_bpermute_b32 v113, v176, v112
	global_store_dwordx4 v[224:225], v[120:123], off offset:256
	s_waitcnt lgkmcnt(0)
	v_add_f32_e32 v112, v112, v113
	v_xor_b32_e32 v113, 32, v222
	v_cmp_lt_i32_e64 s[0:1], v113, v114
	s_nop 1
	v_cndmask_b32_e64 v113, v222, v113, s[0:1]
	v_lshlrev_b32_e32 v177, 2, v113
	ds_bpermute_b32 v113, v177, v112
	s_and_saveexec_b64 s[0:1], s[36:37]
	s_cbranch_execz .LBB0_466
	v_lshlrev_b64 v[114:115], 6, v[208:209]
	v_lshl_add_u64 v[114:115], s[22:23], 0, v[114:115]
	s_waitcnt lgkmcnt(0)
	v_add_f32_e32 v112, v112, v113
	global_store_dword v[114:115], v112, off
